# v28 + non-leader workgroups poll the cross-XCD generation word directly (one fewer memory hop per chip-wide barrier)
# baseline (speedup 1.0000x reference)
; __device__ __forceinline__ unsigned xb_ld(unsigned* p)              { return __hip_atomic_load(p, __ATOMIC_RELAXED, __HIP_MEMORY_SCOPE_AGENT); }
; __device__ __forceinline__ unsigned xb_add(unsigned* p, unsigned v) { return __hip_atomic_fetch_add(p, v, __ATOMIC_RELAXED, __HIP_MEMORY_SCOPE_AGENT); }
; #define XB_SPIN(cond, bar) do { unsigned _sp = 0; while (cond) { __builtin_amdgcn_s_sleep(1); \
;     if ((++_sp & 255u) == 0u) { if (xb_ld(&(bar)[XB_TMO])) break; if (_sp > XB_SPIN_CAP) { atomicAdd(&(bar)[XB_TMO], 1u); break; } } } } while (0)
; __device__ __forceinline__ void xcd_barrier(const XcdBarrier& b) {
;     ...
;         const unsigned old = xb_add(&bar[XB_XSUB(b.x)], 1u);
;         const unsigned gen = old / nloc;
;         if (old + 1u == (gen + 1u) * nloc) {
;             __builtin_amdgcn_fence(__ATOMIC_RELEASE, "agent");
;             asm volatile("s_waitcnt vmcnt(0)" ::: "memory");
;             const unsigned og = xb_add(&bar[XB_TOP], 1u);
;             const unsigned tg = og / nx;
;             if (og + 1u == (tg + 1u) * nx) xb_add(&bar[XB_TOPGEN], 1u);
;             else XB_SPIN(xb_ld(&bar[XB_TOPGEN]) == tg, bar);
;             __builtin_amdgcn_fence(__ATOMIC_ACQUIRE, "agent");
;             xb_add(&bar[XB_XGEN(b.x)], 1u);
;             asm volatile("s_waitcnt vmcnt(0)" ::: "memory");
;         } else {
;             XB_SPIN(xb_ld(&bar[XB_XGEN(b.x)]) == gen, bar);
.LBB0_94:
	s_or_b64 exec, exec, s[8:9]
	v_cvt_f32_u32_e32 v4, v2
	s_waitcnt vmcnt(0)
	v_readfirstlane_b32 s6, v3
	v_sub_u32_e32 v3, 0, v2
	v_rcp_iflag_f32_e32 v4, v4
	v_add_u32_e32 v5, s6, v1
	v_mul_f32_e32 v4, 0x4f7ffffe, v4
	v_cvt_u32_f32_e32 v4, v4
	v_mul_lo_u32 v1, v3, v4
	v_mul_hi_u32 v1, v4, v1
	v_add_u32_e32 v1, v4, v1
	v_mul_hi_u32 v1, v5, v1
	v_mul_lo_u32 v3, v1, v2
	v_sub_u32_e32 v3, v5, v3
	v_add_u32_e32 v4, 1, v1
	v_cmp_ge_u32_e32 vcc, v3, v2
	s_nop 1
	v_cndmask_b32_e32 v1, v1, v4, vcc
	v_sub_u32_e32 v4, v3, v2
	v_cndmask_b32_e32 v3, v3, v4, vcc
	v_add_u32_e32 v4, 1, v1
	v_cmp_ge_u32_e32 vcc, v3, v2
	v_add_u32_e32 v3, 1, v5
	s_nop 0
	v_cndmask_b32_e32 v1, v1, v4, vcc
	v_mul_lo_u32 v4, v2, v1
	v_add_u32_e32 v2, v4, v2
	v_cmp_ne_u32_e32 vcc, v3, v2
	s_and_saveexec_b64 s[6:7], vcc
	s_xor_b64 s[6:7], exec, s[6:7]
	s_cbranch_execz .LBB0_108
	s_movk_i32 s8, 0xd40
	s_mov_b32 s9, 0
	s_lshl_b64 s[8:9], s[8:9], 2
	s_add_u32 s10, s4, s8
	s_addc_u32 s11, s5, s9
	s_waitcnt lgkmcnt(0)
	v_mov_b32_e32 v0, 0
	global_load_dword v2, v0, s[10:11] sc1
	s_waitcnt vmcnt(0)
	v_cmp_eq_u32_e32 vcc, v2, v1
	s_and_saveexec_b64 s[8:9], vcc
	s_cbranch_execz .LBB0_107
	s_mov_b32 s22, 1
	s_mov_b64 s[12:13], 0
	s_branch .LBB0_98

; __device__ __forceinline__ unsigned xb_ld(unsigned* p)              { return __hip_atomic_load(p, __ATOMIC_RELAXED, __HIP_MEMORY_SCOPE_AGENT); }
; __device__ __forceinline__ unsigned xb_add(unsigned* p, unsigned v) { return __hip_atomic_fetch_add(p, v, __ATOMIC_RELAXED, __HIP_MEMORY_SCOPE_AGENT); }
; #define XB_SPIN(cond, bar) do { unsigned _sp = 0; while (cond) { __builtin_amdgcn_s_sleep(1); \
;     if ((++_sp & 255u) == 0u) { if (xb_ld(&(bar)[XB_TMO])) break; if (_sp > XB_SPIN_CAP) { atomicAdd(&(bar)[XB_TMO], 1u); break; } } } } while (0)
; __device__ __forceinline__ void xcd_barrier(const XcdBarrier& b) {
;     ...
;         const unsigned old = xb_add(&bar[XB_XSUB(b.x)], 1u);
;         const unsigned gen = old / nloc;
;         if (old + 1u == (gen + 1u) * nloc) {
;             __builtin_amdgcn_fence(__ATOMIC_RELEASE, "agent");
;             asm volatile("s_waitcnt vmcnt(0)" ::: "memory");
;             const unsigned og = xb_add(&bar[XB_TOP], 1u);
;             const unsigned tg = og / nx;
;             if (og + 1u == (tg + 1u) * nx) xb_add(&bar[XB_TOPGEN], 1u);
;             else XB_SPIN(xb_ld(&bar[XB_TOPGEN]) == tg, bar);
;             __builtin_amdgcn_fence(__ATOMIC_ACQUIRE, "agent");
;             xb_add(&bar[XB_XGEN(b.x)], 1u);
;             asm volatile("s_waitcnt vmcnt(0)" ::: "memory");
;         } else {
;             XB_SPIN(xb_ld(&bar[XB_XGEN(b.x)]) == gen, bar);
.LBB0_289:
	s_or_b64 exec, exec, s[10:11]
	v_cvt_f32_u32_e32 v5, v3
	s_waitcnt vmcnt(0)
	v_readfirstlane_b32 s8, v4
	v_sub_u32_e32 v4, 0, v3
	v_rcp_iflag_f32_e32 v5, v5
	v_add_u32_e32 v6, s8, v0
	v_mul_f32_e32 v5, 0x4f7ffffe, v5
	v_cvt_u32_f32_e32 v5, v5
	v_mul_lo_u32 v0, v4, v5
	v_mul_hi_u32 v0, v5, v0
	v_add_u32_e32 v0, v5, v0
	v_mul_hi_u32 v0, v6, v0
	v_mul_lo_u32 v4, v0, v3
	v_sub_u32_e32 v4, v6, v4
	v_add_u32_e32 v5, 1, v0
	v_cmp_ge_u32_e32 vcc, v4, v3
	s_nop 1
	v_cndmask_b32_e32 v0, v0, v5, vcc
	v_sub_u32_e32 v5, v4, v3
	v_cndmask_b32_e32 v4, v4, v5, vcc
	v_add_u32_e32 v5, 1, v0
	v_cmp_ge_u32_e32 vcc, v4, v3
	v_add_u32_e32 v4, 1, v6
	s_nop 0
	v_cndmask_b32_e32 v0, v0, v5, vcc
	v_mul_lo_u32 v5, v3, v0
	v_add_u32_e32 v3, v5, v3
	v_cmp_ne_u32_e32 vcc, v4, v3
	s_and_saveexec_b64 s[8:9], vcc
	s_xor_b64 s[8:9], exec, s[8:9]
	s_cbranch_execz .LBB0_303
	s_movk_i32 s10, 0xd40
	s_mov_b32 s11, s54
	s_lshl_b64 s[10:11], s[10:11], 2
	s_add_u32 s12, s4, s10
	s_addc_u32 s13, s5, s11
	s_waitcnt lgkmcnt(0)
	global_load_dword v2, v1, s[12:13] sc1
	s_waitcnt vmcnt(0)
	v_cmp_eq_u32_e32 vcc, v2, v0
	s_and_saveexec_b64 s[10:11], vcc
	s_cbranch_execz .LBB0_302
	s_mov_b32 s24, 1
	s_mov_b64 s[14:15], 0
	s_branch .LBB0_293

; __device__ __forceinline__ unsigned xb_ld(unsigned* p)              { return __hip_atomic_load(p, __ATOMIC_RELAXED, __HIP_MEMORY_SCOPE_AGENT); }
; __device__ __forceinline__ unsigned xb_add(unsigned* p, unsigned v) { return __hip_atomic_fetch_add(p, v, __ATOMIC_RELAXED, __HIP_MEMORY_SCOPE_AGENT); }
; #define XB_SPIN(cond, bar) do { unsigned _sp = 0; while (cond) { __builtin_amdgcn_s_sleep(1); \
;     if ((++_sp & 255u) == 0u) { if (xb_ld(&(bar)[XB_TMO])) break; if (_sp > XB_SPIN_CAP) { atomicAdd(&(bar)[XB_TMO], 1u); break; } } } } while (0)
; __device__ __forceinline__ void xcd_barrier(const XcdBarrier& b) {
;     ...
;         const unsigned old = xb_add(&bar[XB_XSUB(b.x)], 1u);
;         const unsigned gen = old / nloc;
;         if (old + 1u == (gen + 1u) * nloc) {
;             __builtin_amdgcn_fence(__ATOMIC_RELEASE, "agent");
;             asm volatile("s_waitcnt vmcnt(0)" ::: "memory");
;             const unsigned og = xb_add(&bar[XB_TOP], 1u);
;             const unsigned tg = og / nx;
;             if (og + 1u == (tg + 1u) * nx) xb_add(&bar[XB_TOPGEN], 1u);
;             else XB_SPIN(xb_ld(&bar[XB_TOPGEN]) == tg, bar);
;             __builtin_amdgcn_fence(__ATOMIC_ACQUIRE, "agent");
;             xb_add(&bar[XB_XGEN(b.x)], 1u);
;             asm volatile("s_waitcnt vmcnt(0)" ::: "memory");
;         } else {
;             XB_SPIN(xb_ld(&bar[XB_XGEN(b.x)]) == gen, bar);
.LBB0_404:
	s_or_b64 exec, exec, s[6:7]
	v_cvt_f32_u32_e32 v5, v3
	s_waitcnt vmcnt(0)
	v_readfirstlane_b32 s4, v4
	v_sub_u32_e32 v4, 0, v3
	v_rcp_iflag_f32_e32 v5, v5
	v_add_u32_e32 v6, s4, v0
	v_mul_f32_e32 v5, 0x4f7ffffe, v5
	v_cvt_u32_f32_e32 v5, v5
	v_mul_lo_u32 v0, v4, v5
	v_mul_hi_u32 v0, v5, v0
	v_add_u32_e32 v0, v5, v0
	v_mul_hi_u32 v0, v6, v0
	v_mul_lo_u32 v4, v0, v3
	v_sub_u32_e32 v4, v6, v4
	v_add_u32_e32 v5, 1, v0
	v_cmp_ge_u32_e32 vcc, v4, v3
	s_nop 1
	v_cndmask_b32_e32 v0, v0, v5, vcc
	v_sub_u32_e32 v5, v4, v3
	v_cndmask_b32_e32 v4, v4, v5, vcc
	v_add_u32_e32 v5, 1, v0
	v_cmp_ge_u32_e32 vcc, v4, v3
	v_add_u32_e32 v4, 1, v6
	s_nop 0
	v_cndmask_b32_e32 v0, v0, v5, vcc
	v_mul_lo_u32 v5, v3, v0
	v_add_u32_e32 v3, v5, v3
	v_cmp_ne_u32_e32 vcc, v4, v3
	s_and_saveexec_b64 s[4:5], vcc
	s_xor_b64 s[4:5], exec, s[4:5]
	s_cbranch_execz .LBB0_418
	s_movk_i32 s6, 0xd40
	s_mov_b32 s7, s54
	s_lshl_b64 s[6:7], s[6:7], 2
	s_add_u32 s8, s2, s6
	s_addc_u32 s9, s3, s7
	s_waitcnt lgkmcnt(0)
	global_load_dword v2, v1, s[8:9] sc1
	s_waitcnt vmcnt(0)
	v_cmp_eq_u32_e32 vcc, v2, v0
	s_and_saveexec_b64 s[6:7], vcc
	s_cbranch_execz .LBB0_417
	s_mov_b32 s20, 1
	s_mov_b64 s[10:11], 0
	s_branch .LBB0_408

; __device__ __forceinline__ unsigned xb_ld(unsigned* p)              { return __hip_atomic_load(p, __ATOMIC_RELAXED, __HIP_MEMORY_SCOPE_AGENT); }
; __device__ __forceinline__ unsigned xb_add(unsigned* p, unsigned v) { return __hip_atomic_fetch_add(p, v, __ATOMIC_RELAXED, __HIP_MEMORY_SCOPE_AGENT); }
; #define XB_SPIN(cond, bar) do { unsigned _sp = 0; while (cond) { __builtin_amdgcn_s_sleep(1); \
;     if ((++_sp & 255u) == 0u) { if (xb_ld(&(bar)[XB_TMO])) break; if (_sp > XB_SPIN_CAP) { atomicAdd(&(bar)[XB_TMO], 1u); break; } } } } while (0)
; __device__ __forceinline__ void xcd_barrier(const XcdBarrier& b) {
;     ...
;         const unsigned old = xb_add(&bar[XB_XSUB(b.x)], 1u);
;         const unsigned gen = old / nloc;
;         if (old + 1u == (gen + 1u) * nloc) {
;             __builtin_amdgcn_fence(__ATOMIC_RELEASE, "agent");
;             asm volatile("s_waitcnt vmcnt(0)" ::: "memory");
;             const unsigned og = xb_add(&bar[XB_TOP], 1u);
;             const unsigned tg = og / nx;
;             if (og + 1u == (tg + 1u) * nx) xb_add(&bar[XB_TOPGEN], 1u);
;             else XB_SPIN(xb_ld(&bar[XB_TOPGEN]) == tg, bar);
;             __builtin_amdgcn_fence(__ATOMIC_ACQUIRE, "agent");
;             xb_add(&bar[XB_XGEN(b.x)], 1u);
;             asm volatile("s_waitcnt vmcnt(0)" ::: "memory");
;         } else {
;             XB_SPIN(xb_ld(&bar[XB_XGEN(b.x)]) == gen, bar);
.LBB0_760:
	s_or_b64 exec, exec, s[6:7]
	v_cvt_f32_u32_e32 v5, v3
	s_waitcnt vmcnt(0)
	v_readfirstlane_b32 s4, v4
	v_sub_u32_e32 v4, 0, v3
	v_rcp_iflag_f32_e32 v5, v5
	v_add_u32_e32 v6, s4, v0
	v_mul_f32_e32 v5, 0x4f7ffffe, v5
	v_cvt_u32_f32_e32 v5, v5
	v_mul_lo_u32 v0, v4, v5
	v_mul_hi_u32 v0, v5, v0
	v_add_u32_e32 v0, v5, v0
	v_mul_hi_u32 v0, v6, v0
	v_mul_lo_u32 v4, v0, v3
	v_sub_u32_e32 v4, v6, v4
	v_add_u32_e32 v5, 1, v0
	v_cmp_ge_u32_e32 vcc, v4, v3
	s_nop 1
	v_cndmask_b32_e32 v0, v0, v5, vcc
	v_sub_u32_e32 v5, v4, v3
	v_cndmask_b32_e32 v4, v4, v5, vcc
	v_add_u32_e32 v5, 1, v0
	v_cmp_ge_u32_e32 vcc, v4, v3
	v_add_u32_e32 v4, 1, v6
	s_nop 0
	v_cndmask_b32_e32 v0, v0, v5, vcc
	v_mul_lo_u32 v5, v3, v0
	v_add_u32_e32 v3, v5, v3
	v_cmp_ne_u32_e32 vcc, v4, v3
	s_and_saveexec_b64 s[4:5], vcc
	s_xor_b64 s[4:5], exec, s[4:5]
	s_cbranch_execz .LBB0_774
	s_movk_i32 s6, 0xd40
	s_mov_b32 s7, s54
	s_lshl_b64 s[6:7], s[6:7], 2
	s_add_u32 s8, s2, s6
	s_addc_u32 s9, s3, s7
	s_waitcnt lgkmcnt(0)
	global_load_dword v2, v1, s[8:9] sc1
	s_waitcnt vmcnt(0)
	v_cmp_eq_u32_e32 vcc, v2, v0
	s_and_saveexec_b64 s[6:7], vcc
	s_cbranch_execz .LBB0_773
	s_mov_b32 s17, 1
	s_mov_b64 s[10:11], 0
	s_branch .LBB0_764
